# attn loops rotated (no unconditional back-branch); group-4 cvt_pk and next-trip scalar glue moved into the row-sum chain's wait-state slots (-7 instrs/tile)
# speedup vs baseline: 1.0099x; 1.0099x over previous
.Lq1_body:
	v_add_co_u32_e32 v2, vcc, 0xfbf00000, v202
	s_nop 1
	v_addc_co_u32_e32 v3, vcc, -1, v203, vcc
	global_load_dwordx4 v[28:31], v[2:3], off offset:-128
	global_load_dwordx4 v[32:35], v[2:3], off
	v_add_co_u32_e32 v2, vcc, 0xffffc000, v202
	s_nop 1
	v_addc_co_u32_e32 v3, vcc, -1, v203, vcc
	global_load_dwordx4 v[4:7], v[2:3], off offset:-128
	global_load_dwordx4 v[12:15], v[2:3], off
	ds_read_b128 v[44:47], v214 offset:35840
	ds_read_b128 v[72:75], v214 offset:35904
	ds_read_b128 v[92:95], v214 offset:40192
	ds_read_b128 v[112:115], v214 offset:40256
	ds_read_b128 v[132:135], v214 offset:44544
	ds_read_b128 v[148:151], v214 offset:44608
	ds_read_b128 v[136:139], v214 offset:48896
	ds_read_b128 v[152:155], v214 offset:48960
	s_waitcnt lgkmcnt(7)
	v_mfma_f32_16x16x32_bf16 v[140:143], v[44:47], v[8:11], 0
	v_mfma_f32_16x16x32_bf16 v[44:47], v[44:47], v[20:23], 0
	s_waitcnt lgkmcnt(1)
	v_mfma_f32_16x16x32_bf16 v[156:159], v[92:95], v[8:11], 0
	v_mfma_f32_16x16x32_bf16 v[92:95], v[92:95], v[20:23], 0
	v_mfma_f32_16x16x32_bf16 v[160:163], v[132:135], v[8:11], 0
	v_mfma_f32_16x16x32_bf16 v[132:135], v[132:135], v[20:23], 0
	v_mfma_f32_16x16x32_bf16 v[164:167], v[136:139], v[8:11], 0
	v_mfma_f32_16x16x32_bf16 v[168:171], v[136:139], v[20:23], 0
	v_mfma_f32_16x16x32_bf16 v[144:147], v[72:75], v[16:19], v[140:143]
	v_mfma_f32_16x16x32_bf16 v[136:139], v[72:75], v[24:27], v[44:47]
	v_mfma_f32_16x16x32_bf16 v[44:47], v[112:115], v[16:19], v[156:159]
	v_mfma_f32_16x16x32_bf16 v[92:95], v[112:115], v[24:27], v[92:95]
	v_mfma_f32_16x16x32_bf16 v[140:143], v[148:151], v[16:19], v[160:163]
	v_mfma_f32_16x16x32_bf16 v[132:135], v[148:151], v[24:27], v[132:135]
	s_waitcnt lgkmcnt(0)
	v_mfma_f32_16x16x32_bf16 v[72:75], v[152:155], v[16:19], v[164:167]
	v_mfma_f32_16x16x32_bf16 v[112:115], v[152:155], v[24:27], v[168:171]
	s_cmp_eq_u32 s98, 0
	s_cbranch_scc1 .LBB0_859
	v_sub_f32_e32 v147, v147, v196
	v_sub_f32_e32 v146, v146, v196
	v_sub_f32_e32 v145, v145, v196
	v_sub_f32_e32 v144, v144, v196
	v_sub_f32_e32 v47, v47, v196
	v_sub_f32_e32 v46, v46, v196
	v_sub_f32_e32 v45, v45, v196
	v_sub_f32_e32 v44, v44, v196
	v_sub_f32_e32 v143, v143, v196
	v_sub_f32_e32 v142, v142, v196
	v_sub_f32_e32 v141, v141, v196
	v_sub_f32_e32 v140, v140, v196
	v_sub_f32_e32 v75, v75, v196
	v_sub_f32_e32 v74, v74, v196
	v_sub_f32_e32 v73, v73, v196
	v_sub_f32_e32 v72, v72, v196
	v_sub_f32_e32 v139, v139, v197
	v_sub_f32_e32 v138, v138, v197
	v_sub_f32_e32 v137, v137, v197
	v_sub_f32_e32 v136, v136, v197
	v_sub_f32_e32 v95, v95, v197
	v_sub_f32_e32 v94, v94, v197
	v_sub_f32_e32 v93, v93, v197
	v_sub_f32_e32 v92, v92, v197
	v_sub_f32_e32 v135, v135, v197
	v_sub_f32_e32 v134, v134, v197
	v_sub_f32_e32 v133, v133, v197
	v_sub_f32_e32 v132, v132, v197
	v_sub_f32_e32 v115, v115, v197
	v_sub_f32_e32 v114, v114, v197
	v_sub_f32_e32 v113, v113, v197
	v_sub_f32_e32 v112, v112, v197

.LBB0_863:
	ds_read_b64_tr_b16 v[148:149], v215 offset:17408
	ds_read_b64_tr_b16 v[152:153], v215 offset:17440
	ds_read_b64_tr_b16 v[156:157], v215 offset:17472
	ds_read_b64_tr_b16 v[160:161], v215 offset:17504
	ds_read_b64_tr_b16 v[150:151], v215 offset:22016
	ds_read_b64_tr_b16 v[154:155], v215 offset:22048
	ds_read_b64_tr_b16 v[158:159], v215 offset:22080
	ds_read_b64_tr_b16 v[162:163], v215 offset:22112
	v_exp_f32_e32 v2, v144
	s_waitcnt lgkmcnt(3)
	v_mfma_f32_16x16x32_bf16 v[164:167], v[36:39], v[148:151], v[128:131]
	v_exp_f32_e32 v222, v145
	v_mfma_f32_16x16x32_bf16 v[148:151], v[60:63], v[148:151], v[120:123]
	ds_read_b64_tr_b16 v[238:239], v215 offset:17536
	ds_read_b64_tr_b16 v[242:243], v215 offset:17568
	ds_read_b64_tr_b16 v[246:247], v215 offset:17600
	ds_read_b64_tr_b16 v[250:251], v215 offset:17632
	ds_read_b64_tr_b16 v[240:241], v215 offset:22144
	ds_read_b64_tr_b16 v[244:245], v215 offset:22176
	ds_read_b64_tr_b16 v[248:249], v215 offset:22208
	ds_read_b64_tr_b16 v[252:253], v215 offset:22240
	v_exp_f32_e32 v224, v146
	s_waitcnt lgkmcnt(8)
	v_mfma_f32_16x16x32_bf16 v[124:127], v[36:39], v[152:155], v[124:127]
	v_exp_f32_e32 v122, v147
	v_mfma_f32_16x16x32_bf16 v[152:155], v[60:63], v[152:155], v[108:111]
	v_exp_f32_e32 v226, v44
	v_mfma_f32_16x16x32_bf16 v[116:119], v[36:39], v[156:159], v[116:119]
	v_exp_f32_e32 v110, v45
	v_mfma_f32_16x16x32_bf16 v[168:171], v[60:63], v[156:159], v[100:103]
	v_exp_f32_e32 v228, v46
	v_mfma_f32_16x16x32_bf16 v[104:107], v[36:39], v[160:163], v[104:107]
	v_exp_f32_e32 v100, v47
	v_mfma_f32_16x16x32_bf16 v[160:163], v[60:63], v[160:163], v[96:99]
	v_cvt_pk_bf16_f32 v44, v2, v222
	v_cvt_pk_bf16_f32 v45, v224, v122
	v_cvt_pk_bf16_f32 v46, v226, v110
	v_cvt_pk_bf16_f32 v47, v228, v100
	v_exp_f32_e32 v96, v140
	s_waitcnt lgkmcnt(0)
	v_mfma_f32_16x16x32_bf16 v[180:183], v[36:39], v[238:241], v[88:91]
	v_exp_f32_e32 v230, v141
	v_mfma_f32_16x16x32_bf16 v[184:187], v[60:63], v[238:241], v[76:79]
	v_exp_f32_e32 v232, v142
	v_mfma_f32_16x16x32_bf16 v[80:83], v[36:39], v[242:245], v[80:83]
	v_exp_f32_e32 v78, v143
	v_mfma_f32_16x16x32_bf16 v[188:191], v[60:63], v[242:245], v[64:67]
	ds_read_b64_tr_b16 v[140:141], v215 offset:26624
	ds_read_b64_tr_b16 v[156:157], v215 offset:26656
	ds_read_b64_tr_b16 v[172:173], v215 offset:26688
	ds_read_b64_tr_b16 v[176:177], v215 offset:26720
	ds_read_b64_tr_b16 v[142:143], v215 offset:31232
	ds_read_b64_tr_b16 v[158:159], v215 offset:31264
	ds_read_b64_tr_b16 v[174:175], v215 offset:31296
	ds_read_b64_tr_b16 v[178:179], v215 offset:31328
	v_exp_f32_e32 v234, v72
	v_mfma_f32_16x16x32_bf16 v[68:71], v[36:39], v[246:249], v[68:71]
	v_exp_f32_e32 v66, v73
	v_mfma_f32_16x16x32_bf16 v[192:195], v[60:63], v[246:249], v[52:55]
	v_exp_f32_e32 v236, v74
	v_mfma_f32_16x16x32_bf16 v[56:59], v[36:39], v[250:253], v[56:59]
	v_exp_f32_e32 v54, v75
	v_mfma_f32_16x16x32_bf16 v[48:51], v[60:63], v[250:253], v[48:51]
	v_cvt_pk_bf16_f32 v72, v96, v230
	v_cvt_pk_bf16_f32 v73, v232, v78
	v_cvt_pk_bf16_f32 v74, v234, v66
	v_cvt_pk_bf16_f32 v75, v236, v54
	v_exp_f32_e32 v3, v136
	s_waitcnt lgkmcnt(0)
	v_mfma_f32_16x16x32_bf16 v[144:147], v[40:43], v[140:143], v[164:167]
	v_exp_f32_e32 v223, v137
	v_mfma_f32_16x16x32_bf16 v[140:143], v[84:87], v[140:143], v[148:151]
	ds_read_b64_tr_b16 v[238:239], v215 offset:26752
	ds_read_b64_tr_b16 v[242:243], v215 offset:26784
	ds_read_b64_tr_b16 v[246:247], v215 offset:26816
	ds_read_b64_tr_b16 v[250:251], v215 offset:26848
	ds_read_b64_tr_b16 v[240:241], v215 offset:31360
	ds_read_b64_tr_b16 v[244:245], v215 offset:31392
	ds_read_b64_tr_b16 v[248:249], v215 offset:31424
	ds_read_b64_tr_b16 v[252:253], v215 offset:31456
	v_exp_f32_e32 v225, v138
	v_mfma_f32_16x16x32_bf16 v[148:151], v[40:43], v[156:159], v[124:127]
	v_exp_f32_e32 v123, v139
	v_mfma_f32_16x16x32_bf16 v[136:139], v[84:87], v[156:159], v[152:155]
	v_exp_f32_e32 v227, v92
	v_mfma_f32_16x16x32_bf16 v[156:159], v[40:43], v[172:175], v[116:119]
	v_exp_f32_e32 v111, v93
	v_mfma_f32_16x16x32_bf16 v[152:155], v[84:87], v[172:175], v[168:171]
	v_exp_f32_e32 v229, v94
	v_mfma_f32_16x16x32_bf16 v[164:167], v[40:43], v[176:179], v[104:107]
	v_exp_f32_e32 v101, v95
	v_mfma_f32_16x16x32_bf16 v[160:163], v[84:87], v[176:179], v[160:163]
	s_nop 0
	v_cvt_pk_bf16_f32 v92, v3, v223
	v_cvt_pk_bf16_f32 v93, v225, v123
	v_cvt_pk_bf16_f32 v94, v227, v111
	v_cvt_pk_bf16_f32 v95, v229, v101
	v_exp_f32_e32 v97, v132
	s_waitcnt lgkmcnt(0)
	v_mfma_f32_16x16x32_bf16 v[172:175], v[40:43], v[238:241], v[180:183]
	v_exp_f32_e32 v231, v133
	v_mfma_f32_16x16x32_bf16 v[168:171], v[84:87], v[238:241], v[184:187]
	v_exp_f32_e32 v233, v134
	v_mfma_f32_16x16x32_bf16 v[176:179], v[40:43], v[242:245], v[80:83]
	v_exp_f32_e32 v79, v135
	v_mfma_f32_16x16x32_bf16 v[132:135], v[84:87], v[242:245], v[188:191]
	v_exp_f32_e32 v235, v112
	v_mfma_f32_16x16x32_bf16 v[184:187], v[40:43], v[246:249], v[68:71]
	v_exp_f32_e32 v67, v113
	v_mfma_f32_16x16x32_bf16 v[180:183], v[84:87], v[246:249], v[192:195]
	v_exp_f32_e32 v237, v114
	v_mfma_f32_16x16x32_bf16 v[192:195], v[40:43], v[250:253], v[56:59]
	v_exp_f32_e32 v55, v115
	v_mfma_f32_16x16x32_bf16 v[188:191], v[84:87], v[250:253], v[48:51]
	s_andn2_b64 vcc, exec, s[0:1]
	s_cbranch_vccnz .LBB0_865
; #define LAS __attribute__((address_space(3)))
; template <bool SAMPLE> __device__ __forceinline__ void attn_unit16(const Ctx& c, LAS unsigned char* lds, int b, int h, int qb, int wave_s) {
;     ...
;     auto store_k = [&](int slot) { if (SAMPLE) { kreg[0] = pack8(kraw[0], kraw[1]); kreg[1] = pack8(kraw[2], kraw[3]); if (!kok) { kreg[0] = (u32x4){0u, 0u, 0u, 0u}; kreg[1] = kreg[0]; } }
;         LAS unsigned char* kb = lds + slot * B_STG + lrow * A_RSK + lck * 16; *(LAS u32x4*)kb = kreg[0]; *(LAS u32x4*)(kb + 128) = kreg[1]; };
;     auto store_v = [&](int slot) { if (SAMPLE) { vreg[0] = pack8(vraw[0], vraw[1]); vreg[1] = pack8(vraw[2], vraw[3]); if (!vok) { vreg[0] = (u32x4){0u, 0u, 0u, 0u}; vreg[1] = vreg[0]; } }
;         LAS unsigned char* vb = lds + slot * B_STG + A_KSZ + lrow * B_RSV + lck * 16; *(LAS u32x4*)vb = vreg[0]; *(LAS u32x4*)(vb + 128) = vreg[1]; };
	v_mov_b32_e32 v0, v210
	s_nop 0
	v_lshlrev_b32_e32 v0, 2, v0
	v_and_b32_e32 v0, 60, v0
	v_and_or_b32 v0, v212, 64, v0
	v_lshlrev_b32_e32 v0, 2, v0
	ds_bpermute_b32 v48, v0, v200
	ds_bpermute_b32 v50, v0, v200 offset:8
	ds_bpermute_b32 v51, v0, v200 offset:12
	ds_bpermute_b32 v49, v0, v200 offset:4
	ds_bpermute_b32 v56, v0, v201
	ds_bpermute_b32 v58, v0, v201 offset:8
	ds_bpermute_b32 v59, v0, v201 offset:12
	ds_bpermute_b32 v57, v0, v201 offset:4
	s_waitcnt lgkmcnt(5)
	v_pk_mul_f32 v[146:147], v[146:147], v[50:51]
	s_waitcnt lgkmcnt(4)
	v_pk_mul_f32 v[144:145], v[144:145], v[48:49]
	v_pk_mul_f32 v[150:151], v[150:151], v[50:51]
	v_pk_mul_f32 v[148:149], v[148:149], v[48:49]
	v_pk_mul_f32 v[158:159], v[158:159], v[50:51]
	v_pk_mul_f32 v[156:157], v[156:157], v[48:49]
	v_pk_mul_f32 v[166:167], v[166:167], v[50:51]
	v_pk_mul_f32 v[164:165], v[164:165], v[48:49]
	v_pk_mul_f32 v[174:175], v[174:175], v[50:51]
	v_pk_mul_f32 v[172:173], v[172:173], v[48:49]
	v_pk_mul_f32 v[178:179], v[178:179], v[50:51]
	v_pk_mul_f32 v[176:177], v[176:177], v[48:49]
	v_pk_mul_f32 v[186:187], v[186:187], v[50:51]
	v_pk_mul_f32 v[184:185], v[184:185], v[48:49]
	v_pk_mul_f32 v[194:195], v[194:195], v[50:51]
	v_pk_mul_f32 v[192:193], v[192:193], v[48:49]
	s_waitcnt lgkmcnt(1)
	v_pk_mul_f32 v[142:143], v[142:143], v[58:59]
	s_waitcnt lgkmcnt(0)
	v_pk_mul_f32 v[140:141], v[140:141], v[56:57]
	v_pk_mul_f32 v[138:139], v[138:139], v[58:59]
	v_pk_mul_f32 v[136:137], v[136:137], v[56:57]
	v_pk_mul_f32 v[154:155], v[154:155], v[58:59]
	v_pk_mul_f32 v[152:153], v[152:153], v[56:57]
	v_pk_mul_f32 v[162:163], v[162:163], v[58:59]
	v_pk_mul_f32 v[160:161], v[160:161], v[56:57]
	v_pk_mul_f32 v[170:171], v[170:171], v[58:59]
	v_pk_mul_f32 v[168:169], v[168:169], v[56:57]
	v_pk_mul_f32 v[134:135], v[134:135], v[58:59]
	v_pk_mul_f32 v[132:133], v[132:133], v[56:57]
	v_pk_mul_f32 v[182:183], v[182:183], v[58:59]
	v_pk_mul_f32 v[180:181], v[180:181], v[56:57]
	v_pk_mul_f32 v[190:191], v[190:191], v[58:59]
	v_pk_mul_f32 v[188:189], v[188:189], v[56:57]
.LBB0_865:
	v_pk_add_f32 v[2:3], v[198:199], v[2:3]
	s_waitcnt vmcnt(0)
	v_pk_add_f32 v[2:3], v[222:223], v[2:3]
	ds_write_b128 v211, v[28:31]
	v_pk_add_f32 v[2:3], v[224:225], v[2:3]
	ds_write_b128 v211, v[32:35] offset:128
	v_pk_add_f32 v[2:3], v[122:123], v[2:3]
	ds_write_b128 v213, v[4:7] offset:53248
	v_pk_add_f32 v[2:3], v[226:227], v[2:3]
	ds_write_b128 v213, v[12:15] offset:53376
	v_pk_add_f32 v[2:3], v[110:111], v[2:3]
	v_cvt_pk_bf16_f32 v112, v97, v231
	v_pk_add_f32 v[2:3], v[228:229], v[2:3]
	v_cvt_pk_bf16_f32 v113, v233, v79
	v_pk_add_f32 v[2:3], v[100:101], v[2:3]
	v_cvt_pk_bf16_f32 v114, v235, v67
	v_pk_add_f32 v[2:3], v[96:97], v[2:3]
	v_cvt_pk_bf16_f32 v115, v237, v55
	v_pk_add_f32 v[2:3], v[230:231], v[2:3]
	s_cmp_lt_u32 s89, s82
	v_pk_add_f32 v[2:3], v[232:233], v[2:3]
	s_nop 0
	v_pk_add_f32 v[2:3], v[78:79], v[2:3]
	s_nop 0
	v_pk_add_f32 v[2:3], v[234:235], v[2:3]
	s_nop 0
	v_pk_add_f32 v[2:3], v[66:67], v[2:3]
	s_nop 0
	v_pk_add_f32 v[2:3], v[236:237], v[2:3]
	s_nop 0
	v_pk_add_f32 v[198:199], v[54:55], v[2:3]
.LBB0_866:
	s_waitcnt lgkmcnt(0)
	s_barrier
	s_cbranch_scc0 .Lq1_h2_nok
	v_add_co_u32_e32 v2, vcc, 0xfbf04000, v202
	s_nop 1
	v_addc_co_u32_e32 v3, vcc, -1, v203, vcc
	global_load_dwordx4 v[28:31], v[2:3], off offset:-128
	global_load_dwordx4 v[32:35], v[2:3], off

.LBB0_879:
	ds_read_b64_tr_b16 v[124:125], v215 offset:53248
	ds_read_b64_tr_b16 v[100:101], v215 offset:53280
	ds_read_b64_tr_b16 v[116:117], v215 offset:53312
	ds_read_b64_tr_b16 v[96:97], v215 offset:53344
	ds_read_b64_tr_b16 v[126:127], v215 offset:57856
	ds_read_b64_tr_b16 v[102:103], v215 offset:57888
	ds_read_b64_tr_b16 v[118:119], v215 offset:57920
	ds_read_b64_tr_b16 v[98:99], v215 offset:57952
	v_exp_f32_e32 v2, v128
	s_waitcnt lgkmcnt(3)
	v_mfma_f32_16x16x32_bf16 v[104:107], v[44:47], v[124:127], v[144:147]
	v_exp_f32_e32 v222, v129
	v_mfma_f32_16x16x32_bf16 v[124:127], v[92:95], v[124:127], v[140:143]
	ds_read_b64_tr_b16 v[238:239], v215 offset:53376
	ds_read_b64_tr_b16 v[242:243], v215 offset:53408
	ds_read_b64_tr_b16 v[246:247], v215 offset:53440
	ds_read_b64_tr_b16 v[250:251], v215 offset:53472
	ds_read_b64_tr_b16 v[240:241], v215 offset:57984
	ds_read_b64_tr_b16 v[244:245], v215 offset:58016
	ds_read_b64_tr_b16 v[248:249], v215 offset:58048
	ds_read_b64_tr_b16 v[252:253], v215 offset:58080
	v_exp_f32_e32 v224, v130
	s_waitcnt lgkmcnt(8)
	v_mfma_f32_16x16x32_bf16 v[148:151], v[44:47], v[100:103], v[148:151]
	v_exp_f32_e32 v142, v131
	v_mfma_f32_16x16x32_bf16 v[100:103], v[92:95], v[100:103], v[136:139]
	v_exp_f32_e32 v226, v36
	v_mfma_f32_16x16x32_bf16 v[156:159], v[44:47], v[116:119], v[156:159]
	v_exp_f32_e32 v138, v37
	v_mfma_f32_16x16x32_bf16 v[76:79], v[92:95], v[116:119], v[152:155]
	v_exp_f32_e32 v228, v38
	v_mfma_f32_16x16x32_bf16 v[164:167], v[44:47], v[96:99], v[164:167]
	v_exp_f32_e32 v154, v39
	v_mfma_f32_16x16x32_bf16 v[96:99], v[92:95], v[96:99], v[160:163]
	v_cvt_pk_bf16_f32 v36, v2, v222
	v_cvt_pk_bf16_f32 v37, v224, v142
	v_cvt_pk_bf16_f32 v38, v226, v138
	v_cvt_pk_bf16_f32 v39, v228, v154
	v_exp_f32_e32 v160, v120
	s_waitcnt lgkmcnt(0)
	v_mfma_f32_16x16x32_bf16 v[52:55], v[44:47], v[238:241], v[172:175]
	v_exp_f32_e32 v230, v121
	v_mfma_f32_16x16x32_bf16 v[68:71], v[92:95], v[238:241], v[168:171]
	v_exp_f32_e32 v232, v122
	v_mfma_f32_16x16x32_bf16 v[176:179], v[44:47], v[242:245], v[176:179]
	v_exp_f32_e32 v170, v123
	v_mfma_f32_16x16x32_bf16 v[48:51], v[92:95], v[242:245], v[132:135]
	ds_read_b64_tr_b16 v[120:121], v215 offset:62464
	ds_read_b64_tr_b16 v[116:117], v215 offset:62496
	ds_read_b64_tr_b16 v[88:89], v215 offset:62528
	ds_read_b64_tr_b16 v[80:81], v215 offset:62560
	ds_read_b64_tr_b16 v[122:123], v216 offset:13824
	ds_read_b64_tr_b16 v[118:119], v216 offset:13856
	ds_read_b64_tr_b16 v[90:91], v216 offset:13888
	ds_read_b64_tr_b16 v[82:83], v216 offset:13920
	v_exp_f32_e32 v234, v40
	v_mfma_f32_16x16x32_bf16 v[184:187], v[44:47], v[246:249], v[184:187]
	v_exp_f32_e32 v134, v41
	v_mfma_f32_16x16x32_bf16 v[56:59], v[92:95], v[246:249], v[180:183]
	v_exp_f32_e32 v236, v42
	v_mfma_f32_16x16x32_bf16 v[192:195], v[44:47], v[250:253], v[192:195]
	v_exp_f32_e32 v182, v43
	v_mfma_f32_16x16x32_bf16 v[188:191], v[92:95], v[250:253], v[188:191]
	v_cvt_pk_bf16_f32 v40, v160, v230
	v_cvt_pk_bf16_f32 v41, v232, v170
	v_cvt_pk_bf16_f32 v42, v234, v134
	v_cvt_pk_bf16_f32 v43, v236, v182
	v_exp_f32_e32 v3, v108
	s_waitcnt lgkmcnt(0)
	v_mfma_f32_16x16x32_bf16 v[128:131], v[72:75], v[120:123], v[104:107]
	v_exp_f32_e32 v223, v109
	v_mfma_f32_16x16x32_bf16 v[120:123], v[112:115], v[120:123], v[124:127]
	ds_read_b64_tr_b16 v[238:239], v215 offset:62592
	ds_read_b64_tr_b16 v[242:243], v215 offset:62624
	ds_read_b64_tr_b16 v[246:247], v215 offset:62656
	ds_read_b64_tr_b16 v[250:251], v215 offset:62688
	ds_read_b64_tr_b16 v[240:241], v216 offset:13952
	ds_read_b64_tr_b16 v[244:245], v216 offset:13984
	ds_read_b64_tr_b16 v[248:249], v216 offset:14016
	ds_read_b64_tr_b16 v[252:253], v216 offset:14048
	v_exp_f32_e32 v225, v110
	v_mfma_f32_16x16x32_bf16 v[124:127], v[72:75], v[116:119], v[148:151]
	v_exp_f32_e32 v143, v111
	v_mfma_f32_16x16x32_bf16 v[108:111], v[112:115], v[116:119], v[100:103]
	v_exp_f32_e32 v227, v60
	v_mfma_f32_16x16x32_bf16 v[116:119], v[72:75], v[88:91], v[156:159]
	v_exp_f32_e32 v139, v61
	v_mfma_f32_16x16x32_bf16 v[100:103], v[112:115], v[88:91], v[76:79]
	v_exp_f32_e32 v229, v62
	v_mfma_f32_16x16x32_bf16 v[104:107], v[72:75], v[80:83], v[164:167]
	v_exp_f32_e32 v155, v63
	v_mfma_f32_16x16x32_bf16 v[96:99], v[112:115], v[80:83], v[96:99]
	s_nop 0
	v_cvt_pk_bf16_f32 v60, v3, v223
	v_cvt_pk_bf16_f32 v61, v225, v143
	v_cvt_pk_bf16_f32 v62, v227, v139
	v_cvt_pk_bf16_f32 v63, v229, v155
	v_exp_f32_e32 v161, v64
	s_waitcnt lgkmcnt(0)
	v_mfma_f32_16x16x32_bf16 v[88:91], v[72:75], v[238:241], v[52:55]
	v_exp_f32_e32 v231, v65
	v_mfma_f32_16x16x32_bf16 v[76:79], v[112:115], v[238:241], v[68:71]
	v_exp_f32_e32 v233, v66
	v_mfma_f32_16x16x32_bf16 v[80:83], v[72:75], v[242:245], v[176:179]
	v_exp_f32_e32 v171, v67
	v_mfma_f32_16x16x32_bf16 v[64:67], v[112:115], v[242:245], v[48:51]
	v_exp_f32_e32 v235, v84
	v_mfma_f32_16x16x32_bf16 v[68:71], v[72:75], v[246:249], v[184:187]
	v_exp_f32_e32 v135, v85
	v_mfma_f32_16x16x32_bf16 v[52:55], v[112:115], v[246:249], v[56:59]
	v_exp_f32_e32 v237, v86
	v_mfma_f32_16x16x32_bf16 v[56:59], v[72:75], v[250:253], v[192:195]
	v_exp_f32_e32 v183, v87
	v_mfma_f32_16x16x32_bf16 v[48:51], v[112:115], v[250:253], v[188:191]
	s_andn2_b64 vcc, exec, s[2:3]
	s_cbranch_vccnz .LBB0_881
; #define LAS __attribute__((address_space(3)))
; #define EXPALL(PF) do { _Pragma("unroll") for (int s_ = 0; s_ < 16 * NQT; ++s_) EXP1(s_); PACK16(PF, 0, 0); PACK16(PF, 0, 1); if (NQT > 1) { PACK16(PF, 1, 0); PACK16(PF, 1, 1); } } while (0)
; template <bool SAMPLE> __device__ __forceinline__ void attn_unit16(const Ctx& c, LAS unsigned char* lds, int b, int h, int qb, int wave_s) {
;     ...
;     if (SAMPLE) { load_kv(0, true); load_kv(0, false); store_k(0); store_v(0); load_kv(1, true); store_k(1); }
;     else { load_kv(0, true); const u32x4 k0a = kreg[0], k0b = kreg[1];
;       load_kv(0, false); load_kv(1, true);
;       LAS unsigned char* kb0 = lds + lrow * A_RSK + lck * 16; *(LAS u32x4*)kb0 = k0a; *(LAS u32x4*)(kb0 + 128) = k0b;
;       store_v(0); store_k(1); }
;     __syncthreads();
;     if (active) { QK16(0); MAX16(0); EXPALL(pfa); }
;     for (int j = 0; j < ntiles; j += 2) {
;         ITER16(j, pfa, pfb, 0, 1);
;         if (j + 1 < ntiles) ITER16(j + 1, pfb, pfa, 1, 0);
;     }
	v_mov_b32_e32 v0, v210
	s_nop 0
	v_lshlrev_b32_e32 v0, 2, v0
	v_and_b32_e32 v0, 60, v0
	v_and_or_b32 v0, v212, 64, v0
	v_lshlrev_b32_e32 v0, 2, v0
	ds_bpermute_b32 v188, v0, v200
	ds_bpermute_b32 v190, v0, v200 offset:8
	ds_bpermute_b32 v191, v0, v200 offset:12
	ds_bpermute_b32 v189, v0, v200 offset:4
	ds_bpermute_b32 v192, v0, v201
	ds_bpermute_b32 v194, v0, v201 offset:8
	ds_bpermute_b32 v195, v0, v201 offset:12
	ds_bpermute_b32 v193, v0, v201 offset:4
	s_waitcnt lgkmcnt(5)
	v_pk_mul_f32 v[130:131], v[130:131], v[190:191]
	s_waitcnt lgkmcnt(4)
	v_pk_mul_f32 v[128:129], v[128:129], v[188:189]
	v_pk_mul_f32 v[126:127], v[126:127], v[190:191]
	v_pk_mul_f32 v[124:125], v[124:125], v[188:189]
	v_pk_mul_f32 v[118:119], v[118:119], v[190:191]
	v_pk_mul_f32 v[116:117], v[116:117], v[188:189]
	v_pk_mul_f32 v[106:107], v[106:107], v[190:191]
	v_pk_mul_f32 v[104:105], v[104:105], v[188:189]
	v_pk_mul_f32 v[90:91], v[90:91], v[190:191]
	v_pk_mul_f32 v[88:89], v[88:89], v[188:189]
	v_pk_mul_f32 v[82:83], v[82:83], v[190:191]
	v_pk_mul_f32 v[80:81], v[80:81], v[188:189]
	v_pk_mul_f32 v[70:71], v[70:71], v[190:191]
	v_pk_mul_f32 v[68:69], v[68:69], v[188:189]
	v_pk_mul_f32 v[58:59], v[58:59], v[190:191]
	v_pk_mul_f32 v[56:57], v[56:57], v[188:189]
	s_waitcnt lgkmcnt(1)
	v_pk_mul_f32 v[122:123], v[122:123], v[194:195]
	s_waitcnt lgkmcnt(0)
	v_pk_mul_f32 v[120:121], v[120:121], v[192:193]
	v_pk_mul_f32 v[110:111], v[110:111], v[194:195]
	v_pk_mul_f32 v[108:109], v[108:109], v[192:193]
	v_pk_mul_f32 v[102:103], v[102:103], v[194:195]
	v_pk_mul_f32 v[100:101], v[100:101], v[192:193]
	v_pk_mul_f32 v[98:99], v[98:99], v[194:195]
	v_pk_mul_f32 v[96:97], v[96:97], v[192:193]
	v_pk_mul_f32 v[78:79], v[78:79], v[194:195]
	v_pk_mul_f32 v[76:77], v[76:77], v[192:193]
	v_pk_mul_f32 v[66:67], v[66:67], v[194:195]
	v_pk_mul_f32 v[64:65], v[64:65], v[192:193]
	v_pk_mul_f32 v[54:55], v[54:55], v[194:195]
	v_pk_mul_f32 v[52:53], v[52:53], v[192:193]
	v_pk_mul_f32 v[50:51], v[50:51], v[194:195]
	v_pk_mul_f32 v[48:49], v[48:49], v[192:193]
.LBB0_881:
	v_pk_add_f32 v[2:3], v[198:199], v[2:3]
	s_waitcnt vmcnt(0)
	v_pk_add_f32 v[2:3], v[222:223], v[2:3]
	ds_write_b128 v211, v[28:31] offset:35840
	v_pk_add_f32 v[2:3], v[224:225], v[2:3]
	ds_write_b128 v211, v[32:35] offset:35968
	v_pk_add_f32 v[2:3], v[142:143], v[2:3]
	ds_write_b128 v213, v[4:7] offset:17408
	v_pk_add_f32 v[2:3], v[226:227], v[2:3]
	ds_write_b128 v213, v[12:15] offset:17536
	v_pk_add_f32 v[2:3], v[138:139], v[2:3]
	v_cvt_pk_bf16_f32 v84, v161, v231
	v_pk_add_f32 v[2:3], v[228:229], v[2:3]
	v_cvt_pk_bf16_f32 v85, v233, v171
	v_pk_add_f32 v[2:3], v[154:155], v[2:3]
	v_cvt_pk_bf16_f32 v86, v235, v135
	v_pk_add_f32 v[2:3], v[160:161], v[2:3]
	v_cvt_pk_bf16_f32 v87, v237, v183
	v_pk_add_f32 v[2:3], v[230:231], v[2:3]
	v_lshl_add_u64 v[202:203], v[202:203], 0, s[10:11]
	v_pk_add_f32 v[2:3], v[232:233], v[2:3]
	s_addk_i32 s87, 0x80
	v_pk_add_f32 v[2:3], v[170:171], v[2:3]
	s_mov_b32 s89, s88
	v_pk_add_f32 v[2:3], v[234:235], v[2:3]
	s_add_i32 s88, s88, 2
	v_pk_add_f32 v[2:3], v[134:135], v[2:3]
	s_cmp_lt_u32 s88, s84
	v_pk_add_f32 v[2:3], v[236:237], v[2:3]
	s_nop 0
	v_pk_add_f32 v[198:199], v[182:183], v[2:3]
.LBB0_882:
	s_waitcnt lgkmcnt(0)
	s_barrier
	s_cbranch_scc1 .Lq1_body
	s_branch .Lq1_last
.Lq1_h2_pvonly:
	ds_read_b64_tr_b16 v[64:65], v215 offset:53248
	ds_read_b64_tr_b16 v[108:109], v215 offset:53280
	ds_read_b64_tr_b16 v[120:121], v215 offset:53312
	ds_read_b64_tr_b16 v[128:129], v215 offset:53344
	ds_read_b64_tr_b16 v[66:67], v215 offset:57856
	ds_read_b64_tr_b16 v[110:111], v215 offset:57888
	ds_read_b64_tr_b16 v[122:123], v215 offset:57920
	ds_read_b64_tr_b16 v[130:131], v215 offset:57952
	s_waitcnt lgkmcnt(3)
	v_mfma_f32_16x16x32_bf16 v[124:127], v[44:47], v[64:67], v[144:147]
	v_mfma_f32_16x16x32_bf16 v[64:67], v[92:95], v[64:67], v[140:143]
	s_waitcnt lgkmcnt(2)
	v_mfma_f32_16x16x32_bf16 v[100:103], v[44:47], v[108:111], v[148:151]
	v_mfma_f32_16x16x32_bf16 v[108:111], v[92:95], v[108:111], v[136:139]
	s_waitcnt lgkmcnt(1)
	v_mfma_f32_16x16x32_bf16 v[116:119], v[44:47], v[120:123], v[156:159]
	v_mfma_f32_16x16x32_bf16 v[96:99], v[92:95], v[120:123], v[152:155]
	s_waitcnt lgkmcnt(0)
	v_mfma_f32_16x16x32_bf16 v[104:107], v[44:47], v[128:131], v[164:167]
	v_mfma_f32_16x16x32_bf16 v[76:79], v[92:95], v[128:131], v[160:163]
	ds_read_b64_tr_b16 v[120:121], v215 offset:53376
	ds_read_b64_tr_b16 v[128:129], v215 offset:53408
	ds_read_b64_tr_b16 v[88:89], v215 offset:53440
	ds_read_b64_tr_b16 v[80:81], v215 offset:53472
	ds_read_b64_tr_b16 v[122:123], v215 offset:57984
	ds_read_b64_tr_b16 v[130:131], v215 offset:58016
	ds_read_b64_tr_b16 v[90:91], v215 offset:58048
	ds_read_b64_tr_b16 v[82:83], v215 offset:58080
	s_waitcnt lgkmcnt(3)
	v_mfma_f32_16x16x32_bf16 v[52:55], v[44:47], v[120:123], v[172:175]
	v_mfma_f32_16x16x32_bf16 v[68:71], v[92:95], v[120:123], v[168:171]
	s_waitcnt lgkmcnt(2)
	v_mfma_f32_16x16x32_bf16 v[48:51], v[44:47], v[128:131], v[176:179]
	v_mfma_f32_16x16x32_bf16 v[56:59], v[92:95], v[128:131], v[132:135]
	s_waitcnt lgkmcnt(1)
	v_mfma_f32_16x16x32_bf16 v[218:221], v[44:47], v[88:91], v[184:187]
	v_mfma_f32_16x16x32_bf16 v[222:225], v[92:95], v[88:91], v[180:183]
	s_waitcnt lgkmcnt(0)
	v_mfma_f32_16x16x32_bf16 v[226:229], v[44:47], v[80:83], v[192:195]
	v_mfma_f32_16x16x32_bf16 v[230:233], v[92:95], v[80:83], v[188:191]
	ds_read_b64_tr_b16 v[120:121], v215 offset:62464
	ds_read_b64_tr_b16 v[88:89], v215 offset:62496
	ds_read_b64_tr_b16 v[80:81], v215 offset:62528
	ds_read_b64_tr_b16 v[234:235], v215 offset:62560
	ds_read_b64_tr_b16 v[122:123], v216 offset:13824
	ds_read_b64_tr_b16 v[90:91], v216 offset:13856
	ds_read_b64_tr_b16 v[82:83], v216 offset:13888
	ds_read_b64_tr_b16 v[236:237], v216 offset:13920
	s_waitcnt lgkmcnt(3)
	v_mfma_f32_16x16x32_bf16 v[128:131], v[72:75], v[120:123], v[124:127]
	v_mfma_f32_16x16x32_bf16 v[120:123], v[112:115], v[120:123], v[64:67]
	s_waitcnt lgkmcnt(2)
	v_mfma_f32_16x16x32_bf16 v[124:127], v[72:75], v[88:91], v[100:103]
	v_mfma_f32_16x16x32_bf16 v[108:111], v[112:115], v[88:91], v[108:111]
	s_waitcnt lgkmcnt(1)
	v_mfma_f32_16x16x32_bf16 v[116:119], v[72:75], v[80:83], v[116:119]
	v_mfma_f32_16x16x32_bf16 v[100:103], v[112:115], v[80:83], v[96:99]
	s_waitcnt lgkmcnt(0)
	v_mfma_f32_16x16x32_bf16 v[104:107], v[72:75], v[234:237], v[104:107]
	v_mfma_f32_16x16x32_bf16 v[96:99], v[112:115], v[234:237], v[76:79]
	ds_read_b64_tr_b16 v[64:65], v215 offset:62592
	ds_read_b64_tr_b16 v[234:235], v215 offset:62624
	ds_read_b64_tr_b16 v[238:239], v215 offset:62656
	ds_read_b64_tr_b16 v[242:243], v215 offset:62688
	ds_read_b64_tr_b16 v[66:67], v216 offset:13952
	ds_read_b64_tr_b16 v[236:237], v216 offset:13984
	ds_read_b64_tr_b16 v[240:241], v216 offset:14016
	ds_read_b64_tr_b16 v[244:245], v216 offset:14048
	s_waitcnt lgkmcnt(3)
	v_mfma_f32_16x16x32_bf16 v[88:91], v[72:75], v[64:67], v[52:55]
	v_mfma_f32_16x16x32_bf16 v[76:79], v[112:115], v[64:67], v[68:71]
	s_waitcnt lgkmcnt(2)
	v_mfma_f32_16x16x32_bf16 v[80:83], v[72:75], v[234:237], v[48:51]
	v_mfma_f32_16x16x32_bf16 v[64:67], v[112:115], v[234:237], v[56:59]
	s_waitcnt lgkmcnt(1)
	v_mfma_f32_16x16x32_bf16 v[68:71], v[72:75], v[238:241], v[218:221]
	v_mfma_f32_16x16x32_bf16 v[52:55], v[112:115], v[238:241], v[222:225]
	s_waitcnt lgkmcnt(0)
	v_mfma_f32_16x16x32_bf16 v[56:59], v[72:75], v[242:245], v[226:229]
	v_mfma_f32_16x16x32_bf16 v[48:51], v[112:115], v[242:245], v[230:233]
	s_mov_b64 s[2:3], 0
	s_waitcnt vmcnt(0)
	ds_write_b128 v211, v[28:31] offset:35840
	ds_write_b128 v211, v[32:35] offset:35968
	ds_write_b128 v213, v[4:7] offset:17408
	ds_write_b128 v213, v[12:15] offset:17536
	v_lshl_add_u64 v[202:203], v[202:203], 0, s[10:11]
	s_addk_i32 s87, 0x80
	s_mov_b32 s89, s88
	s_add_i32 s88, s88, 2
	s_cmp_lt_u32 s88, s84
	s_branch .LBB0_882

.Lq2_body:
	v_add_co_u32_e32 v2, vcc, 0xfbf00000, v202
	s_nop 1
	v_addc_co_u32_e32 v3, vcc, -1, v203, vcc
	global_load_dwordx4 v[28:31], v[2:3], off offset:-128
	global_load_dwordx4 v[32:35], v[2:3], off
	v_add_co_u32_e32 v2, vcc, 0xffffc000, v202
	s_nop 1
	v_addc_co_u32_e32 v3, vcc, -1, v203, vcc
	global_load_dwordx4 v[4:7], v[2:3], off offset:-128
	global_load_dwordx4 v[16:19], v[2:3], off
	ds_read_b128 v[44:47], v221 offset:35840
	ds_read_b128 v[56:59], v221 offset:35904
	ds_read_b128 v[88:91], v221 offset:40192
	ds_read_b128 v[96:99], v221 offset:40256
	ds_read_b128 v[132:135], v221 offset:44544
	ds_read_b128 v[148:151], v221 offset:44608
	ds_read_b128 v[136:139], v221 offset:48896
	ds_read_b128 v[152:155], v221 offset:48960
	s_waitcnt lgkmcnt(7)
	v_mfma_f32_16x16x32_bf16 v[140:143], v[44:47], v[8:11], 0
	v_mfma_f32_16x16x32_bf16 v[44:47], v[44:47], v[20:23], 0
	s_waitcnt lgkmcnt(5)
	v_mfma_f32_16x16x32_bf16 v[156:159], v[88:91], v[8:11], 0
	v_mfma_f32_16x16x32_bf16 v[88:91], v[88:91], v[20:23], 0
	s_waitcnt lgkmcnt(3)
	v_mfma_f32_16x16x32_bf16 v[160:163], v[132:135], v[8:11], 0
	v_mfma_f32_16x16x32_bf16 v[132:135], v[132:135], v[20:23], 0
	s_waitcnt lgkmcnt(1)
	v_mfma_f32_16x16x32_bf16 v[164:167], v[136:139], v[8:11], 0
	v_mfma_f32_16x16x32_bf16 v[168:171], v[136:139], v[20:23], 0
	v_mfma_f32_16x16x32_bf16 v[144:147], v[56:59], v[12:15], v[140:143]
	v_mfma_f32_16x16x32_bf16 v[136:139], v[56:59], v[24:27], v[44:47]
	v_mfma_f32_16x16x32_bf16 v[44:47], v[96:99], v[12:15], v[156:159]
	v_mfma_f32_16x16x32_bf16 v[88:91], v[96:99], v[24:27], v[88:91]
	v_mfma_f32_16x16x32_bf16 v[140:143], v[148:151], v[12:15], v[160:163]
	v_mfma_f32_16x16x32_bf16 v[132:135], v[148:151], v[24:27], v[132:135]
	s_waitcnt lgkmcnt(0)
	v_mfma_f32_16x16x32_bf16 v[56:59], v[152:155], v[12:15], v[164:167]
	v_mfma_f32_16x16x32_bf16 v[96:99], v[152:155], v[24:27], v[168:171]
	v_cmp_neq_f32_e32 vcc, 0, v196
	v_cmp_neq_f32_e64 s[0:1], 0, v197
	s_or_b64 vcc, vcc, s[0:1]
	s_cbranch_vccz .LBB0_925
	v_sub_f32_e32 v147, v147, v196
	v_sub_f32_e32 v146, v146, v196
	v_sub_f32_e32 v145, v145, v196
	v_sub_f32_e32 v144, v144, v196
	v_sub_f32_e32 v47, v47, v196
	v_sub_f32_e32 v46, v46, v196
	v_sub_f32_e32 v45, v45, v196
	v_sub_f32_e32 v44, v44, v196
	v_sub_f32_e32 v143, v143, v196
	v_sub_f32_e32 v142, v142, v196
	v_sub_f32_e32 v141, v141, v196
	v_sub_f32_e32 v140, v140, v196
	v_sub_f32_e32 v59, v59, v196
	v_sub_f32_e32 v58, v58, v196
	v_sub_f32_e32 v57, v57, v196
	v_sub_f32_e32 v56, v56, v196
	v_sub_f32_e32 v139, v139, v197
	v_sub_f32_e32 v138, v138, v197
	v_sub_f32_e32 v137, v137, v197
	v_sub_f32_e32 v136, v136, v197
	v_sub_f32_e32 v91, v91, v197
	v_sub_f32_e32 v90, v90, v197
	v_sub_f32_e32 v89, v89, v197
	v_sub_f32_e32 v88, v88, v197
	v_sub_f32_e32 v135, v135, v197
	v_sub_f32_e32 v134, v134, v197
	v_sub_f32_e32 v133, v133, v197
	v_sub_f32_e32 v132, v132, v197
	v_sub_f32_e32 v99, v99, v197
	v_sub_f32_e32 v98, v98, v197
	v_sub_f32_e32 v97, v97, v197
	v_sub_f32_e32 v96, v96, v197

.LBB0_929:
	ds_read_b64_tr_b16 v[148:149], v222 offset:17408
	ds_read_b64_tr_b16 v[152:153], v222 offset:17440
	ds_read_b64_tr_b16 v[156:157], v222 offset:17472
	ds_read_b64_tr_b16 v[160:161], v222 offset:17504
	ds_read_b64_tr_b16 v[150:151], v222 offset:22016
	ds_read_b64_tr_b16 v[154:155], v222 offset:22048
	ds_read_b64_tr_b16 v[158:159], v222 offset:22080
	ds_read_b64_tr_b16 v[162:163], v222 offset:22112
	v_exp_f32_e32 v2, v144
	s_waitcnt lgkmcnt(3)
	v_mfma_f32_16x16x32_bf16 v[164:167], v[36:39], v[148:151], v[128:131]
	s_nop 2
	v_exp_f32_e32 v128, v145
	v_mfma_f32_16x16x32_bf16 v[148:151], v[48:51], v[148:151], v[124:127]
	s_nop 2
	v_exp_f32_e32 v124, v146
	s_waitcnt lgkmcnt(2)
	v_mfma_f32_16x16x32_bf16 v[168:171], v[36:39], v[152:155], v[120:123]
	s_nop 2
	v_exp_f32_e32 v120, v147
	v_mfma_f32_16x16x32_bf16 v[152:155], v[48:51], v[152:155], v[116:119]
	s_nop 2
	v_exp_f32_e32 v116, v44
	s_waitcnt lgkmcnt(1)
	v_mfma_f32_16x16x32_bf16 v[172:175], v[36:39], v[156:159], v[112:115]
	s_nop 2
	v_exp_f32_e32 v112, v45
	v_mfma_f32_16x16x32_bf16 v[176:179], v[48:51], v[156:159], v[108:111]
	s_nop 2
	v_exp_f32_e32 v108, v46
	s_waitcnt lgkmcnt(0)
	v_mfma_f32_16x16x32_bf16 v[180:183], v[36:39], v[160:163], v[104:107]
	s_nop 2
	v_exp_f32_e32 v104, v47
	v_mfma_f32_16x16x32_bf16 v[160:163], v[48:51], v[160:163], v[100:103]
	ds_read_b64_tr_b16 v[144:145], v222 offset:17536
	ds_read_b64_tr_b16 v[156:157], v222 offset:17568
	ds_read_b64_tr_b16 v[184:185], v222 offset:17600
	ds_read_b64_tr_b16 v[188:189], v222 offset:17632
	ds_read_b64_tr_b16 v[146:147], v222 offset:22144
	ds_read_b64_tr_b16 v[158:159], v222 offset:22176
	ds_read_b64_tr_b16 v[186:187], v222 offset:22208
	ds_read_b64_tr_b16 v[190:191], v222 offset:22240
	v_cvt_pk_bf16_f32 v44, v2, v128
	v_cvt_pk_bf16_f32 v45, v124, v120
	v_cvt_pk_bf16_f32 v46, v116, v112
	v_cvt_pk_bf16_f32 v47, v108, v104
	v_exp_f32_e32 v100, v140
	s_waitcnt lgkmcnt(3)
	v_mfma_f32_16x16x32_bf16 v[192:195], v[36:39], v[144:147], v[92:95]
	s_nop 2
	v_exp_f32_e32 v92, v141
	v_mfma_f32_16x16x32_bf16 v[226:229], v[48:51], v[144:147], v[84:87]
	s_nop 2
	v_exp_f32_e32 v84, v142
	s_waitcnt lgkmcnt(2)
	v_mfma_f32_16x16x32_bf16 v[230:233], v[36:39], v[156:159], v[80:83]
	s_nop 2
	v_exp_f32_e32 v80, v143
	v_mfma_f32_16x16x32_bf16 v[234:237], v[48:51], v[156:159], v[72:75]
	s_nop 2
	v_exp_f32_e32 v72, v56
	s_waitcnt lgkmcnt(1)
	v_mfma_f32_16x16x32_bf16 v[238:241], v[36:39], v[184:187], v[68:71]
	s_nop 2
	v_exp_f32_e32 v68, v57
	v_mfma_f32_16x16x32_bf16 v[242:245], v[48:51], v[184:187], v[64:67]
	s_nop 2
	v_exp_f32_e32 v64, v58
	s_waitcnt lgkmcnt(0)
	v_mfma_f32_16x16x32_bf16 v[246:249], v[36:39], v[188:191], v[60:63]
	s_nop 2
	v_exp_f32_e32 v60, v59
	v_mfma_f32_16x16x32_bf16 v[52:55], v[48:51], v[188:191], v[52:55]
	ds_read_b64_tr_b16 v[140:141], v222 offset:26624
	ds_read_b64_tr_b16 v[156:157], v222 offset:26656
	ds_read_b64_tr_b16 v[184:185], v222 offset:26688
	ds_read_b64_tr_b16 v[188:189], v222 offset:26720
	ds_read_b64_tr_b16 v[142:143], v222 offset:31232
	ds_read_b64_tr_b16 v[158:159], v222 offset:31264
	ds_read_b64_tr_b16 v[186:187], v222 offset:31296
	ds_read_b64_tr_b16 v[190:191], v222 offset:31328
	v_cvt_pk_bf16_f32 v56, v100, v92
	v_cvt_pk_bf16_f32 v57, v84, v80
	v_cvt_pk_bf16_f32 v58, v72, v68
	v_cvt_pk_bf16_f32 v59, v64, v60
	v_exp_f32_e32 v3, v136
	s_waitcnt lgkmcnt(3)
	v_mfma_f32_16x16x32_bf16 v[144:147], v[40:43], v[140:143], v[164:167]
	v_exp_f32_e32 v129, v137
	v_mfma_f32_16x16x32_bf16 v[140:143], v[76:79], v[140:143], v[148:151]
	v_exp_f32_e32 v125, v138
	s_waitcnt lgkmcnt(2)
	v_mfma_f32_16x16x32_bf16 v[148:151], v[40:43], v[156:159], v[168:171]
	v_exp_f32_e32 v121, v139
	v_mfma_f32_16x16x32_bf16 v[136:139], v[76:79], v[156:159], v[152:155]
	v_exp_f32_e32 v117, v88
	s_waitcnt lgkmcnt(1)
	v_mfma_f32_16x16x32_bf16 v[156:159], v[40:43], v[184:187], v[172:175]
	v_exp_f32_e32 v113, v89
	v_mfma_f32_16x16x32_bf16 v[152:155], v[76:79], v[184:187], v[176:179]
	v_exp_f32_e32 v109, v90
	s_waitcnt lgkmcnt(0)
	v_mfma_f32_16x16x32_bf16 v[164:167], v[40:43], v[188:191], v[180:183]
	v_exp_f32_e32 v105, v91
	v_mfma_f32_16x16x32_bf16 v[160:163], v[76:79], v[188:191], v[160:163]
	ds_read_b64_tr_b16 v[168:169], v222 offset:26752
	ds_read_b64_tr_b16 v[180:181], v222 offset:26784
	ds_read_b64_tr_b16 v[188:189], v222 offset:26816
	ds_read_b64_tr_b16 v[250:251], v222 offset:26848
	ds_read_b64_tr_b16 v[170:171], v222 offset:31360
	ds_read_b64_tr_b16 v[182:183], v222 offset:31392
	ds_read_b64_tr_b16 v[190:191], v222 offset:31424
	ds_read_b64_tr_b16 v[252:253], v222 offset:31456
	v_cvt_pk_bf16_f32 v88, v3, v129
	v_cvt_pk_bf16_f32 v89, v125, v121
	v_cvt_pk_bf16_f32 v90, v117, v113
	v_cvt_pk_bf16_f32 v91, v109, v105
	v_exp_f32_e32 v101, v132
	s_waitcnt lgkmcnt(3)
	v_mfma_f32_16x16x32_bf16 v[172:175], v[40:43], v[168:171], v[192:195]
	v_exp_f32_e32 v93, v133
	v_mfma_f32_16x16x32_bf16 v[168:171], v[76:79], v[168:171], v[226:229]
	v_exp_f32_e32 v85, v134
	s_waitcnt lgkmcnt(2)
	v_mfma_f32_16x16x32_bf16 v[176:179], v[40:43], v[180:183], v[230:233]
	v_exp_f32_e32 v81, v135
	v_mfma_f32_16x16x32_bf16 v[132:135], v[76:79], v[180:183], v[234:237]
	v_exp_f32_e32 v73, v96
	s_waitcnt lgkmcnt(1)
	v_mfma_f32_16x16x32_bf16 v[184:187], v[40:43], v[188:191], v[238:241]
	v_exp_f32_e32 v69, v97
	v_mfma_f32_16x16x32_bf16 v[180:183], v[76:79], v[188:191], v[242:245]
	v_exp_f32_e32 v65, v98
	s_waitcnt lgkmcnt(0)
	v_mfma_f32_16x16x32_bf16 v[192:195], v[40:43], v[250:253], v[246:249]
	v_exp_f32_e32 v61, v99
	v_mfma_f32_16x16x32_bf16 v[188:191], v[76:79], v[250:253], v[52:55]
	s_andn2_b64 vcc, exec, s[0:1]
	s_cbranch_vccnz .LBB0_931
	v_mov_b32_e32 v0, v218
	s_nop 0
	v_lshlrev_b32_e32 v0, 2, v0
	v_and_or_b32 v0, v0, 60, v215
	v_lshlrev_b32_e32 v0, 2, v0
	ds_bpermute_b32 v52, v0, v198
	ds_bpermute_b32 v54, v0, v198 offset:8
	ds_bpermute_b32 v55, v0, v198 offset:12
	ds_bpermute_b32 v53, v0, v198 offset:4
	ds_bpermute_b32 v62, v0, v199
	ds_bpermute_b32 v66, v0, v199 offset:8
	ds_bpermute_b32 v67, v0, v199 offset:12
	ds_bpermute_b32 v63, v0, v199 offset:4
	s_waitcnt lgkmcnt(5)
	v_pk_mul_f32 v[146:147], v[146:147], v[54:55]
	s_waitcnt lgkmcnt(4)
	v_pk_mul_f32 v[144:145], v[144:145], v[52:53]
	v_pk_mul_f32 v[150:151], v[150:151], v[54:55]
	v_pk_mul_f32 v[148:149], v[148:149], v[52:53]
	v_pk_mul_f32 v[158:159], v[158:159], v[54:55]
	v_pk_mul_f32 v[156:157], v[156:157], v[52:53]
	v_pk_mul_f32 v[166:167], v[166:167], v[54:55]
	v_pk_mul_f32 v[164:165], v[164:165], v[52:53]
	v_pk_mul_f32 v[174:175], v[174:175], v[54:55]
	v_pk_mul_f32 v[172:173], v[172:173], v[52:53]
	v_pk_mul_f32 v[178:179], v[178:179], v[54:55]
	v_pk_mul_f32 v[176:177], v[176:177], v[52:53]
	v_pk_mul_f32 v[186:187], v[186:187], v[54:55]
	v_pk_mul_f32 v[184:185], v[184:185], v[52:53]
	v_pk_mul_f32 v[194:195], v[194:195], v[54:55]
	v_pk_mul_f32 v[192:193], v[192:193], v[52:53]
	s_waitcnt lgkmcnt(1)
	v_pk_mul_f32 v[142:143], v[142:143], v[66:67]
	s_waitcnt lgkmcnt(0)
	v_pk_mul_f32 v[140:141], v[140:141], v[62:63]
	v_pk_mul_f32 v[138:139], v[138:139], v[66:67]
	v_pk_mul_f32 v[136:137], v[136:137], v[62:63]
	v_pk_mul_f32 v[154:155], v[154:155], v[66:67]
	v_pk_mul_f32 v[152:153], v[152:153], v[62:63]
	v_pk_mul_f32 v[162:163], v[162:163], v[66:67]
	v_pk_mul_f32 v[160:161], v[160:161], v[62:63]
	v_pk_mul_f32 v[170:171], v[170:171], v[66:67]
	v_pk_mul_f32 v[168:169], v[168:169], v[62:63]
	v_pk_mul_f32 v[134:135], v[134:135], v[66:67]
	v_pk_mul_f32 v[132:133], v[132:133], v[62:63]
	v_pk_mul_f32 v[182:183], v[182:183], v[66:67]
	v_pk_mul_f32 v[180:181], v[180:181], v[62:63]
	v_pk_mul_f32 v[190:191], v[190:191], v[66:67]
	v_pk_mul_f32 v[188:189], v[188:189], v[62:63]
.LBB0_931:
	v_pk_add_f32 v[2:3], v[200:201], v[2:3]
	s_waitcnt vmcnt(0)
	v_pk_add_f32 v[2:3], v[128:129], v[2:3]
	ds_write_b128 v219, v[28:31]
	v_pk_add_f32 v[2:3], v[124:125], v[2:3]
	ds_write_b128 v219, v[32:35] offset:128
	v_pk_add_f32 v[2:3], v[120:121], v[2:3]
	ds_write_b128 v225, v[4:7] offset:53248
	v_pk_add_f32 v[2:3], v[116:117], v[2:3]
	ds_write_b128 v225, v[16:19] offset:53376
	v_pk_add_f32 v[2:3], v[112:113], v[2:3]
	v_cvt_pk_bf16_f32 v96, v101, v93
	v_pk_add_f32 v[2:3], v[108:109], v[2:3]
	v_cvt_pk_bf16_f32 v97, v85, v81
	v_pk_add_f32 v[2:3], v[104:105], v[2:3]
	v_cvt_pk_bf16_f32 v98, v73, v69
	v_pk_add_f32 v[2:3], v[100:101], v[2:3]
	v_cvt_pk_bf16_f32 v99, v65, v61
	v_pk_add_f32 v[2:3], v[92:93], v[2:3]
	s_cmp_lt_u32 s82, s56
	v_pk_add_f32 v[2:3], v[84:85], v[2:3]
	s_nop 0
	v_pk_add_f32 v[2:3], v[80:81], v[2:3]
	s_nop 0
	v_pk_add_f32 v[2:3], v[72:73], v[2:3]
	s_nop 0
	v_pk_add_f32 v[2:3], v[68:69], v[2:3]
	s_nop 0
	v_pk_add_f32 v[2:3], v[64:65], v[2:3]
	s_nop 0
	v_pk_add_f32 v[200:201], v[60:61], v[2:3]

.LBB0_945:
	ds_read_b64_tr_b16 v[120:121], v222 offset:53248
	ds_read_b64_tr_b16 v[108:109], v222 offset:53280
	ds_read_b64_tr_b16 v[112:113], v222 offset:53312
	ds_read_b64_tr_b16 v[100:101], v222 offset:53344
	ds_read_b64_tr_b16 v[122:123], v222 offset:57856
	ds_read_b64_tr_b16 v[110:111], v222 offset:57888
	ds_read_b64_tr_b16 v[114:115], v222 offset:57920
	ds_read_b64_tr_b16 v[102:103], v222 offset:57952
	v_exp_f32_e32 v2, v128
	s_waitcnt lgkmcnt(3)
	v_mfma_f32_16x16x32_bf16 v[104:107], v[44:47], v[120:123], v[144:147]
	s_nop 2
	v_exp_f32_e32 v144, v129
	v_mfma_f32_16x16x32_bf16 v[120:123], v[88:91], v[120:123], v[140:143]
	s_nop 2
	v_exp_f32_e32 v140, v130
	s_waitcnt lgkmcnt(2)
	v_mfma_f32_16x16x32_bf16 v[84:87], v[44:47], v[108:111], v[148:151]
	s_nop 2
	v_exp_f32_e32 v148, v131
	v_mfma_f32_16x16x32_bf16 v[108:111], v[88:91], v[108:111], v[136:139]
	s_nop 2
	v_exp_f32_e32 v136, v36
	s_waitcnt lgkmcnt(1)
	v_mfma_f32_16x16x32_bf16 v[92:95], v[44:47], v[112:115], v[156:159]
	s_nop 2
	v_exp_f32_e32 v156, v37
	v_mfma_f32_16x16x32_bf16 v[80:83], v[88:91], v[112:115], v[152:155]
	s_nop 2
	v_exp_f32_e32 v152, v38
	s_waitcnt lgkmcnt(0)
	v_mfma_f32_16x16x32_bf16 v[64:67], v[44:47], v[100:103], v[164:167]
	s_nop 2
	v_exp_f32_e32 v164, v39
	v_mfma_f32_16x16x32_bf16 v[100:103], v[88:91], v[100:103], v[160:163]
	ds_read_b64_tr_b16 v[128:129], v222 offset:53376
	ds_read_b64_tr_b16 v[112:113], v222 offset:53408
	ds_read_b64_tr_b16 v[68:69], v222 offset:53440
	ds_read_b64_tr_b16 v[52:53], v222 offset:53472
	ds_read_b64_tr_b16 v[130:131], v222 offset:57984
	ds_read_b64_tr_b16 v[114:115], v222 offset:58016
	ds_read_b64_tr_b16 v[70:71], v222 offset:58048
	ds_read_b64_tr_b16 v[54:55], v222 offset:58080
	v_cvt_pk_bf16_f32 v36, v2, v144
	v_cvt_pk_bf16_f32 v37, v140, v148
	v_cvt_pk_bf16_f32 v38, v136, v156
	v_cvt_pk_bf16_f32 v39, v152, v164
	v_exp_f32_e32 v160, v124
	s_waitcnt lgkmcnt(3)
	v_mfma_f32_16x16x32_bf16 v[60:63], v[44:47], v[128:131], v[172:175]
	s_nop 2
	v_exp_f32_e32 v172, v125
	v_mfma_f32_16x16x32_bf16 v[226:229], v[88:91], v[128:131], v[168:171]
	s_nop 2
	v_exp_f32_e32 v168, v126
	s_waitcnt lgkmcnt(2)
	v_mfma_f32_16x16x32_bf16 v[230:233], v[44:47], v[112:115], v[176:179]
	s_nop 2
	v_exp_f32_e32 v176, v127
	v_mfma_f32_16x16x32_bf16 v[234:237], v[88:91], v[112:115], v[132:135]
	s_nop 2
	v_exp_f32_e32 v132, v40
	s_waitcnt lgkmcnt(1)
	v_mfma_f32_16x16x32_bf16 v[238:241], v[44:47], v[68:71], v[184:187]
	s_nop 2
	v_exp_f32_e32 v184, v41
	v_mfma_f32_16x16x32_bf16 v[242:245], v[88:91], v[68:71], v[180:183]
	s_nop 2
	v_exp_f32_e32 v180, v42
	s_waitcnt lgkmcnt(0)
	v_mfma_f32_16x16x32_bf16 v[246:249], v[44:47], v[52:55], v[192:195]
	s_nop 2
	v_exp_f32_e32 v192, v43
	v_mfma_f32_16x16x32_bf16 v[188:191], v[88:91], v[52:55], v[188:191]
	ds_read_b64_tr_b16 v[124:125], v222 offset:62464
	ds_read_b64_tr_b16 v[112:113], v222 offset:62496
	ds_read_b64_tr_b16 v[68:69], v222 offset:62528
	ds_read_b64_tr_b16 v[52:53], v222 offset:62560
	ds_read_b64_tr_b16 v[126:127], v223 offset:13824
	ds_read_b64_tr_b16 v[114:115], v223 offset:13856
	ds_read_b64_tr_b16 v[70:71], v223 offset:13888
	ds_read_b64_tr_b16 v[54:55], v223 offset:13920
	v_cvt_pk_bf16_f32 v40, v160, v172
	v_cvt_pk_bf16_f32 v41, v168, v176
	v_cvt_pk_bf16_f32 v42, v132, v184
	v_cvt_pk_bf16_f32 v43, v180, v192
	v_exp_f32_e32 v3, v116
	s_waitcnt lgkmcnt(3)
	v_mfma_f32_16x16x32_bf16 v[128:131], v[56:59], v[124:127], v[104:107]
	v_exp_f32_e32 v145, v117
	v_mfma_f32_16x16x32_bf16 v[124:127], v[96:99], v[124:127], v[120:123]
	v_exp_f32_e32 v141, v118
	s_waitcnt lgkmcnt(2)
	v_mfma_f32_16x16x32_bf16 v[120:123], v[56:59], v[112:115], v[84:87]
	v_exp_f32_e32 v149, v119
	v_mfma_f32_16x16x32_bf16 v[116:119], v[96:99], v[112:115], v[108:111]
	v_exp_f32_e32 v137, v48
	s_waitcnt lgkmcnt(1)
	v_mfma_f32_16x16x32_bf16 v[112:115], v[56:59], v[68:71], v[92:95]
	v_exp_f32_e32 v157, v49
	v_mfma_f32_16x16x32_bf16 v[108:111], v[96:99], v[68:71], v[80:83]
	v_exp_f32_e32 v153, v50
	s_waitcnt lgkmcnt(0)
	v_mfma_f32_16x16x32_bf16 v[104:107], v[56:59], v[52:55], v[64:67]
	v_exp_f32_e32 v165, v51
	v_mfma_f32_16x16x32_bf16 v[100:103], v[96:99], v[52:55], v[100:103]
	ds_read_b64_tr_b16 v[84:85], v222 offset:62592
	ds_read_b64_tr_b16 v[64:65], v222 offset:62624
	ds_read_b64_tr_b16 v[52:53], v222 offset:62656
	ds_read_b64_tr_b16 v[250:251], v222 offset:62688
	ds_read_b64_tr_b16 v[86:87], v223 offset:13952
	ds_read_b64_tr_b16 v[66:67], v223 offset:13984
	ds_read_b64_tr_b16 v[54:55], v223 offset:14016
	ds_read_b64_tr_b16 v[252:253], v223 offset:14048
	v_cvt_pk_bf16_f32 v48, v3, v145
	v_cvt_pk_bf16_f32 v49, v141, v149
	v_cvt_pk_bf16_f32 v50, v137, v157
	v_cvt_pk_bf16_f32 v51, v153, v165
	v_exp_f32_e32 v161, v72
	s_waitcnt lgkmcnt(3)
	v_mfma_f32_16x16x32_bf16 v[92:95], v[56:59], v[84:87], v[60:63]
	v_exp_f32_e32 v173, v73
	v_mfma_f32_16x16x32_bf16 v[84:87], v[96:99], v[84:87], v[226:229]
	v_exp_f32_e32 v169, v74
	s_waitcnt lgkmcnt(2)
	v_mfma_f32_16x16x32_bf16 v[80:83], v[56:59], v[64:67], v[230:233]
	v_exp_f32_e32 v177, v75
	v_mfma_f32_16x16x32_bf16 v[72:75], v[96:99], v[64:67], v[234:237]
	v_exp_f32_e32 v133, v76
	s_waitcnt lgkmcnt(1)
	v_mfma_f32_16x16x32_bf16 v[68:71], v[56:59], v[52:55], v[238:241]
	v_exp_f32_e32 v185, v77
	v_mfma_f32_16x16x32_bf16 v[64:67], v[96:99], v[52:55], v[242:245]
	v_exp_f32_e32 v181, v78
	s_waitcnt lgkmcnt(0)
	v_mfma_f32_16x16x32_bf16 v[60:63], v[56:59], v[250:253], v[246:249]
	v_exp_f32_e32 v193, v79
	v_mfma_f32_16x16x32_bf16 v[52:55], v[96:99], v[250:253], v[188:191]
	s_andn2_b64 vcc, exec, s[2:3]
	s_cbranch_vccnz .LBB0_947
; #define LAS __attribute__((address_space(3)))
; #define EXPALL(PF) do { _Pragma("unroll") for (int s_ = 0; s_ < 16 * NQT; ++s_) EXP1(s_); PACK16(PF, 0, 0); PACK16(PF, 0, 1); if (NQT > 1) { PACK16(PF, 1, 0); PACK16(PF, 1, 1); } } while (0)
; template <bool SAMPLE> __device__ __forceinline__ void attn_unit16(const Ctx& c, LAS unsigned char* lds, int b, int h, int qb, int wave_s) {
;     ...
;     if (SAMPLE) { load_kv(0, true); load_kv(0, false); store_k(0); store_v(0); load_kv(1, true); store_k(1); }
;     else { load_kv(0, true); const u32x4 k0a = kreg[0], k0b = kreg[1];
;       load_kv(0, false); load_kv(1, true);
;       LAS unsigned char* kb0 = lds + lrow * A_RSK + lck * 16; *(LAS u32x4*)kb0 = k0a; *(LAS u32x4*)(kb0 + 128) = k0b;
;       store_v(0); store_k(1); }
;     __syncthreads();
;     if (active) { QK16(0); MAX16(0); EXPALL(pfa); }
;     for (int j = 0; j < ntiles; j += 2) {
;         ITER16(j, pfa, pfb, 0, 1);
;         if (j + 1 < ntiles) ITER16(j + 1, pfb, pfa, 1, 0);
;     }
	v_mov_b32_e32 v0, v218
	s_nop 0
	v_lshlrev_b32_e32 v0, 2, v0
	v_and_or_b32 v0, v0, 60, v215
	v_lshlrev_b32_e32 v0, 2, v0
	ds_bpermute_b32 v188, v0, v198
	ds_bpermute_b32 v190, v0, v198 offset:8
	ds_bpermute_b32 v191, v0, v198 offset:12
	ds_bpermute_b32 v189, v0, v198 offset:4
	ds_bpermute_b32 v194, v0, v199
	ds_bpermute_b32 v182, v0, v199 offset:8
	ds_bpermute_b32 v183, v0, v199 offset:12
	ds_bpermute_b32 v195, v0, v199 offset:4
	s_waitcnt lgkmcnt(5)
	v_pk_mul_f32 v[130:131], v[130:131], v[190:191]
	s_waitcnt lgkmcnt(4)
	v_pk_mul_f32 v[128:129], v[128:129], v[188:189]
	v_pk_mul_f32 v[122:123], v[122:123], v[190:191]
	v_pk_mul_f32 v[120:121], v[120:121], v[188:189]
	v_pk_mul_f32 v[114:115], v[114:115], v[190:191]
	v_pk_mul_f32 v[112:113], v[112:113], v[188:189]
	v_pk_mul_f32 v[106:107], v[106:107], v[190:191]
	v_pk_mul_f32 v[104:105], v[104:105], v[188:189]
	v_pk_mul_f32 v[94:95], v[94:95], v[190:191]
	v_pk_mul_f32 v[92:93], v[92:93], v[188:189]
	v_pk_mul_f32 v[82:83], v[82:83], v[190:191]
	v_pk_mul_f32 v[80:81], v[80:81], v[188:189]
	v_pk_mul_f32 v[70:71], v[70:71], v[190:191]
	v_pk_mul_f32 v[68:69], v[68:69], v[188:189]
	v_pk_mul_f32 v[62:63], v[62:63], v[190:191]
	v_pk_mul_f32 v[60:61], v[60:61], v[188:189]
	s_waitcnt lgkmcnt(1)
	v_pk_mul_f32 v[126:127], v[126:127], v[182:183]
	s_waitcnt lgkmcnt(0)
	v_pk_mul_f32 v[124:125], v[124:125], v[194:195]
	v_pk_mul_f32 v[118:119], v[118:119], v[182:183]
	v_pk_mul_f32 v[116:117], v[116:117], v[194:195]
	v_pk_mul_f32 v[110:111], v[110:111], v[182:183]
	v_pk_mul_f32 v[108:109], v[108:109], v[194:195]
	v_pk_mul_f32 v[102:103], v[102:103], v[182:183]
	v_pk_mul_f32 v[100:101], v[100:101], v[194:195]
	v_pk_mul_f32 v[86:87], v[86:87], v[182:183]
	v_pk_mul_f32 v[84:85], v[84:85], v[194:195]
	v_pk_mul_f32 v[74:75], v[74:75], v[182:183]
	v_pk_mul_f32 v[72:73], v[72:73], v[194:195]
	v_pk_mul_f32 v[66:67], v[66:67], v[182:183]
	v_pk_mul_f32 v[64:65], v[64:65], v[194:195]
	v_pk_mul_f32 v[54:55], v[54:55], v[182:183]
	v_pk_mul_f32 v[52:53], v[52:53], v[194:195]
.LBB0_947:
	v_pk_add_f32 v[2:3], v[200:201], v[2:3]
	s_waitcnt vmcnt(0)
	v_pk_add_f32 v[2:3], v[144:145], v[2:3]
	ds_write_b128 v219, v[28:31] offset:35840
	v_pk_add_f32 v[2:3], v[140:141], v[2:3]
	ds_write_b128 v219, v[32:35] offset:35968
	v_pk_add_f32 v[2:3], v[148:149], v[2:3]
	ds_write_b128 v220, v[4:7] offset:17408
	v_pk_add_f32 v[2:3], v[136:137], v[2:3]
	ds_write_b128 v220, v[16:19] offset:17536
	v_pk_add_f32 v[2:3], v[156:157], v[2:3]
	v_cvt_pk_bf16_f32 v76, v161, v173
	v_pk_add_f32 v[2:3], v[152:153], v[2:3]
	v_cvt_pk_bf16_f32 v77, v169, v177
	v_pk_add_f32 v[2:3], v[164:165], v[2:3]
	v_cvt_pk_bf16_f32 v78, v133, v185
	v_pk_add_f32 v[2:3], v[160:161], v[2:3]
	v_cvt_pk_bf16_f32 v79, v181, v193
	v_pk_add_f32 v[2:3], v[172:173], v[2:3]
	v_lshl_add_u64 v[202:203], v[202:203], 0, s[10:11]
	v_pk_add_f32 v[2:3], v[168:169], v[2:3]
	s_addk_i32 s80, 0x80
	v_pk_add_f32 v[2:3], v[176:177], v[2:3]
	s_mov_b32 s82, s81
	v_pk_add_f32 v[2:3], v[132:133], v[2:3]
	s_add_i32 s81, s81, 2
	v_pk_add_f32 v[2:3], v[184:185], v[2:3]
	s_cmp_lt_u32 s81, s61
	v_pk_add_f32 v[2:3], v[180:181], v[2:3]
	s_nop 0
	v_pk_add_f32 v[200:201], v[192:193], v[2:3]

.Lq2_h2_pvonly:
	ds_read_b64_tr_b16 v[72:73], v222 offset:53248
	ds_read_b64_tr_b16 v[116:117], v222 offset:53280
	ds_read_b64_tr_b16 v[124:125], v222 offset:53312
	ds_read_b64_tr_b16 v[128:129], v222 offset:53344
	ds_read_b64_tr_b16 v[74:75], v222 offset:57856
	ds_read_b64_tr_b16 v[118:119], v222 offset:57888
	ds_read_b64_tr_b16 v[126:127], v222 offset:57920
	ds_read_b64_tr_b16 v[130:131], v222 offset:57952
	s_waitcnt lgkmcnt(3)
	v_mfma_f32_16x16x32_bf16 v[120:123], v[44:47], v[72:75], v[144:147]
	v_mfma_f32_16x16x32_bf16 v[72:75], v[88:91], v[72:75], v[140:143]
	s_waitcnt lgkmcnt(2)
	v_mfma_f32_16x16x32_bf16 v[108:111], v[44:47], v[116:119], v[148:151]
	v_mfma_f32_16x16x32_bf16 v[116:119], v[88:91], v[116:119], v[136:139]
	s_waitcnt lgkmcnt(1)
	v_mfma_f32_16x16x32_bf16 v[112:115], v[44:47], v[124:127], v[156:159]
	v_mfma_f32_16x16x32_bf16 v[100:103], v[88:91], v[124:127], v[152:155]
	s_waitcnt lgkmcnt(0)
	v_mfma_f32_16x16x32_bf16 v[104:107], v[44:47], v[128:131], v[164:167]
	v_mfma_f32_16x16x32_bf16 v[84:87], v[88:91], v[128:131], v[160:163]
	ds_read_b64_tr_b16 v[124:125], v222 offset:53376
	ds_read_b64_tr_b16 v[128:129], v222 offset:53408
	ds_read_b64_tr_b16 v[92:93], v222 offset:53440
	ds_read_b64_tr_b16 v[80:81], v222 offset:53472
	ds_read_b64_tr_b16 v[126:127], v222 offset:57984
	ds_read_b64_tr_b16 v[130:131], v222 offset:58016
	ds_read_b64_tr_b16 v[94:95], v222 offset:58048
	ds_read_b64_tr_b16 v[82:83], v222 offset:58080
	s_waitcnt lgkmcnt(3)
	v_mfma_f32_16x16x32_bf16 v[64:67], v[44:47], v[124:127], v[172:175]
	v_mfma_f32_16x16x32_bf16 v[68:71], v[88:91], v[124:127], v[168:171]
	s_waitcnt lgkmcnt(2)
	v_mfma_f32_16x16x32_bf16 v[52:55], v[44:47], v[128:131], v[176:179]
	v_mfma_f32_16x16x32_bf16 v[60:63], v[88:91], v[128:131], v[132:135]
	s_waitcnt lgkmcnt(1)
	v_mfma_f32_16x16x32_bf16 v[226:229], v[44:47], v[92:95], v[184:187]
	v_mfma_f32_16x16x32_bf16 v[230:233], v[88:91], v[92:95], v[180:183]
	s_waitcnt lgkmcnt(0)
	v_mfma_f32_16x16x32_bf16 v[234:237], v[44:47], v[80:83], v[192:195]
	v_mfma_f32_16x16x32_bf16 v[238:241], v[88:91], v[80:83], v[188:191]
	ds_read_b64_tr_b16 v[124:125], v222 offset:62464
	ds_read_b64_tr_b16 v[92:93], v222 offset:62496
	ds_read_b64_tr_b16 v[80:81], v222 offset:62528
	ds_read_b64_tr_b16 v[242:243], v222 offset:62560
	ds_read_b64_tr_b16 v[126:127], v223 offset:13824
	ds_read_b64_tr_b16 v[94:95], v223 offset:13856
	ds_read_b64_tr_b16 v[82:83], v223 offset:13888
	ds_read_b64_tr_b16 v[244:245], v223 offset:13920
	s_waitcnt lgkmcnt(3)
	v_mfma_f32_16x16x32_bf16 v[128:131], v[56:59], v[124:127], v[120:123]
	v_mfma_f32_16x16x32_bf16 v[124:127], v[96:99], v[124:127], v[72:75]
	s_waitcnt lgkmcnt(2)
	v_mfma_f32_16x16x32_bf16 v[120:123], v[56:59], v[92:95], v[108:111]
	v_mfma_f32_16x16x32_bf16 v[116:119], v[96:99], v[92:95], v[116:119]
	s_waitcnt lgkmcnt(1)
	v_mfma_f32_16x16x32_bf16 v[112:115], v[56:59], v[80:83], v[112:115]
	v_mfma_f32_16x16x32_bf16 v[108:111], v[96:99], v[80:83], v[100:103]
	s_waitcnt lgkmcnt(0)
	v_mfma_f32_16x16x32_bf16 v[104:107], v[56:59], v[242:245], v[104:107]
	v_mfma_f32_16x16x32_bf16 v[100:103], v[96:99], v[242:245], v[84:87]
	ds_read_b64_tr_b16 v[72:73], v222 offset:62592
	ds_read_b64_tr_b16 v[242:243], v222 offset:62624
	ds_read_b64_tr_b16 v[246:247], v222 offset:62656
	ds_read_b64_tr_b16 v[250:251], v222 offset:62688
	ds_read_b64_tr_b16 v[74:75], v223 offset:13952
	ds_read_b64_tr_b16 v[244:245], v223 offset:13984
	ds_read_b64_tr_b16 v[248:249], v223 offset:14016
	ds_read_b64_tr_b16 v[252:253], v223 offset:14048
	s_waitcnt lgkmcnt(3)
	v_mfma_f32_16x16x32_bf16 v[92:95], v[56:59], v[72:75], v[64:67]
	v_mfma_f32_16x16x32_bf16 v[84:87], v[96:99], v[72:75], v[68:71]
	s_waitcnt lgkmcnt(2)
	v_mfma_f32_16x16x32_bf16 v[80:83], v[56:59], v[242:245], v[52:55]
	v_mfma_f32_16x16x32_bf16 v[72:75], v[96:99], v[242:245], v[60:63]
	s_waitcnt lgkmcnt(1)
	v_mfma_f32_16x16x32_bf16 v[68:71], v[56:59], v[246:249], v[226:229]
	v_mfma_f32_16x16x32_bf16 v[64:67], v[96:99], v[246:249], v[230:233]
	s_waitcnt lgkmcnt(0)
	v_mfma_f32_16x16x32_bf16 v[60:63], v[56:59], v[250:253], v[234:237]
	v_mfma_f32_16x16x32_bf16 v[52:55], v[96:99], v[250:253], v[238:241]
	s_mov_b64 s[2:3], 0
	s_waitcnt vmcnt(0)
	ds_write_b128 v219, v[28:31] offset:35840
	ds_write_b128 v219, v[32:35] offset:35968
	ds_write_b128 v220, v[4:7] offset:17408
	ds_write_b128 v220, v[16:19] offset:17536
	v_lshl_add_u64 v[202:203], v[202:203], 0, s[10:11]
	s_addk_i32 s80, 0x80
	s_mov_b32 s82, s81
	s_add_i32 s81, s81, 2
	s_cmp_lt_u32 s81, s61
	s_branch .LBB0_948
